# P4 rows remapped: each workgroup normalises 128 consecutive tokens of the batch its XCD produced in the scan phase (L2/MALL locality)
# speedup vs baseline: 1.0015x; 1.0015x over previous
.LBB0_406:
	s_cmp_lt_i32 s40, 5
	s_cselect_b64 s[8:9], -1, 0
	s_and_b64 s[12:13], s[8:9], s[6:7]
	s_andn2_b64 vcc, exec, s[12:13]
	s_cbranch_vccnz .LBB0_411
	v_lshrrev_b32_e32 v0, 5, v158
	v_and_b32_e32 v0, 30, v0
	s_and_b32 s3, s2, 7
	s_lshl_b32 s3, s3, 12
	s_lshr_b32 s8, s2, 3
	s_lshl_b32 s8, s8, 7
	s_add_i32 s3, s3, s8
	v_lshl_add_u32 v16, v0, 3, s3
	v_add_u32_e32 v200, 14, v16
	s_mov_b32 s3, 0x8000
	s_mov_b64 s[6:7], s[0:1]
	v_cmp_gt_i32_e32 vcc, s3, v16
	s_and_saveexec_b64 s[14:15], vcc
	s_cbranch_execz .LBB0_410
	s_load_dwordx2 s[8:9], s[6:7], 0x38
	v_lshlrev_b32_e32 v0, 6, v158
	v_and_b32_e32 v17, 0x3c0, v0
	s_load_dwordx2 s[6:7], s[6:7], 0x68
	v_lshlrev_b32_e32 v18, 10, v158
	s_waitcnt lgkmcnt(0)
	global_load_dwordx4 v[0:3], v17, s[8:9] offset:48
	global_load_dwordx4 v[4:7], v17, s[8:9] offset:32
	global_load_dwordx4 v[8:11], v17, s[8:9] offset:16
	global_load_dwordx4 v[12:15], v17, s[8:9]
	s_waitcnt vmcnt(0)
	v_and_b32_e32 v33, 0x3000, v18
	v_mbcnt_lo_u32_b32 v18, -1, 0
	v_mbcnt_hi_u32_b32 v18, -1, v18
	v_and_b32_e32 v19, 64, v18
	v_add_u32_e32 v19, 64, v19
	v_xor_b32_e32 v20, 1, v18
	v_cmp_lt_i32_e32 vcc, v20, v19
	s_load_dword s3, s[0:1], 0x78
	v_and_b32_e32 v17, 63, v158
	v_cndmask_b32_e32 v20, v18, v20, vcc
	v_lshlrev_b32_e32 v34, 2, v20
	v_xor_b32_e32 v20, 2, v18
	v_cmp_lt_i32_e32 vcc, v20, v19
	s_waitcnt lgkmcnt(0)
	s_mov_b32 s16, 2
	s_mov_b64 s[8:9], 0x12000000
	v_cndmask_b32_e32 v20, v18, v20, vcc
	v_lshlrev_b32_e32 v35, 2, v20
	v_xor_b32_e32 v20, 4, v18
	v_cmp_lt_i32_e32 vcc, v20, v19
	s_ashr_i32 s17, s16, 31
	v_bfe_u32 v32, v158, 4, 2
	v_cndmask_b32_e32 v20, v18, v20, vcc
	v_lshlrev_b32_e32 v36, 2, v20
	v_xor_b32_e32 v20, 8, v18
	v_cmp_lt_i32_e32 vcc, v20, v19
	v_mov_b32_e32 v19, 0
	s_lshl_b64 s[18:19], s[16:17], 11
	v_cndmask_b32_e32 v18, v18, v20, vcc
	v_lshlrev_b32_e32 v37, 2, v18
	v_lshlrev_b32_e32 v18, 5, v158
	v_and_b32_e32 v18, 0x60, v18
	v_lshl_add_u64 v[20:21], s[6:7], 0, v[18:19]
	v_lshlrev_b32_e32 v18, 5, v17
	v_ashrrev_i32_e32 v17, 31, v16
	v_lshlrev_b64 v[22:23], 11, v[16:17]
	v_lshlrev_b64 v[24:25], 12, v[16:17]
	v_lshl_add_u64 v[20:21], v[20:21], 0, s[8:9]
	v_lshl_add_u64 v[22:23], s[6:7], 0, v[22:23]
	v_lshl_add_u64 v[24:25], s[6:7], 0, v[24:25]
	s_lshl_b64 s[20:21], s[16:17], 12
	s_mov_b64 s[22:23], 0
	s_mov_b32 s3, 0x3fffc
	s_movk_i32 s17, 0xffe
	s_mov_b64 s[24:25], 0xa000000
	s_mov_b32 s33, 0xa000000
	s_mov_b64 s[26:27], 0x6000000
	s_mov_b32 s34, 0x6000000
	s_movk_i32 s35, 0xfff
	s_mov_b64 s[28:29], 0xa001000
	s_mov_b32 s36, 0xa001000
	s_mov_b64 s[30:31], 0x6000800
	v_mov_b32_e32 v17, 0x358637bd
	s_mov_b32 s37, 0xf800000
	v_mov_b32_e32 v38, 0x260
	s_movk_i32 s38, 0x7fff
.LBB0_409:
	v_lshrrev_b32_e32 v30, 10, v16
	v_lshl_add_u64 v[26:27], v[24:25], 0, v[18:19]
	v_lshl_add_u64 v[28:29], v[22:23], 0, v[18:19]
	v_and_or_b32 v31, v30, s3, v32
	v_lshl_add_u64 v[52:53], v[26:27], 0, s[24:25]
	v_add_co_u32_e32 v30, vcc, s33, v26
	v_lshl_add_u64 v[54:55], v[26:27], 0, s[28:29]
	v_lshl_add_u64 v[56:57], v[28:29], 0, s[30:31]
	global_load_dwordx4 v[40:43], v[52:53], off offset:16
	global_load_dwordx4 v[44:47], v[54:55], off offset:16
	global_load_dwordx4 v[48:51], v[56:57], off offset:16
	v_lshl_or_b32 v52, v31, 14, v33
	v_addc_co_u32_e32 v31, vcc, 0, v27, vcc
	v_add_co_u32_e32 v26, vcc, s36, v26
	v_add_u32_e32 v39, 1, v16
	v_and_or_b32 v70, v16, s17, v52
	v_addc_co_u32_e32 v27, vcc, 0, v27, vcc
	v_lshl_add_u64 v[68:69], v[28:29], 0, s[26:27]
	v_add_co_u32_e32 v28, vcc, s34, v28
	v_and_or_b32 v72, v39, s35, v52
	global_load_dwordx4 v[52:55], v[26:27], off offset:-4096
	global_load_dwordx4 v[56:59], v[26:27], off
	v_ashrrev_i32_e32 v71, 31, v70
	v_addc_co_u32_e32 v29, vcc, 0, v29, vcc
	v_ashrrev_i32_e32 v73, 31, v72
	global_load_dwordx4 v[60:63], v[68:69], off offset:16
	global_load_dwordx4 v[64:67], v[28:29], off
	v_lshlrev_b64 v[74:75], 7, v[70:71]
	v_lshlrev_b64 v[72:73], 7, v[72:73]
	global_load_dwordx4 v[68:71], v[28:29], off offset:2048
	v_lshl_add_u64 v[28:29], v[20:21], 0, v[74:75]
	v_lshl_add_u64 v[88:89], v[20:21], 0, v[72:73]
	global_load_dwordx4 v[72:75], v[28:29], off
	global_load_dwordx4 v[76:79], v[28:29], off offset:16
	global_load_dwordx4 v[80:83], v[88:89], off
	global_load_dwordx4 v[84:87], v[88:89], off offset:16
	v_add_u32_e32 v16, s16, v16
	v_cmp_lt_i32_e32 vcc, v200, v16
	s_or_b64 s[22:23], vcc, s[22:23]
	v_lshl_add_u64 v[22:23], v[22:23], 0, s[18:19]
	v_lshl_add_u64 v[24:25], v[24:25], 0, s[20:21]
	s_waitcnt vmcnt(11)
	v_lshlrev_b32_e32 v88, 16, v43
	v_and_b32_e32 v89, 0xffff0000, v43
	v_lshlrev_b32_e32 v90, 16, v42
	v_and_b32_e32 v91, 0xffff0000, v42
	v_lshlrev_b32_e32 v42, 16, v41
	v_and_b32_e32 v43, 0xffff0000, v41
	v_lshlrev_b32_e32 v92, 16, v40
	v_and_b32_e32 v93, 0xffff0000, v40
	s_waitcnt vmcnt(10)
	v_lshlrev_b32_e32 v40, 16, v47
	v_and_b32_e32 v41, 0xffff0000, v47
	s_waitcnt vmcnt(9)
	v_lshlrev_b32_e32 v28, 16, v51
	v_and_b32_e32 v29, 0xffff0000, v51
	v_lshlrev_b32_e32 v94, 16, v46
	v_and_b32_e32 v95, 0xffff0000, v46
	v_lshlrev_b32_e32 v46, 16, v50
	v_and_b32_e32 v47, 0xffff0000, v50
	v_lshlrev_b32_e32 v50, 16, v45
	v_and_b32_e32 v51, 0xffff0000, v45
	v_lshlrev_b32_e32 v96, 16, v49
	v_and_b32_e32 v97, 0xffff0000, v49
	v_lshlrev_b32_e32 v98, 16, v44
	v_and_b32_e32 v99, 0xffff0000, v44
	v_lshlrev_b32_e32 v44, 16, v48
	v_and_b32_e32 v45, 0xffff0000, v48
	v_mul_f32_e32 v39, 0xbfb8aa3b, v46
	v_mul_f32_e32 v104, 0xbfb8aa3b, v47
	v_mul_f32_e32 v105, 0xbfb8aa3b, v96
	v_mul_f32_e32 v106, 0xbfb8aa3b, v97
	v_mul_f32_e32 v107, 0xbfb8aa3b, v44
	v_mul_f32_e32 v108, 0xbfb8aa3b, v45
	v_mul_f32_e32 v109, 0xbfb8aa3b, v28
	v_mul_f32_e32 v110, 0xbfb8aa3b, v29
	s_waitcnt vmcnt(8)
	v_lshlrev_b32_e32 v48, 16, v55
	v_and_b32_e32 v49, 0xffff0000, v55
	v_lshlrev_b32_e32 v100, 16, v54
	v_and_b32_e32 v101, 0xffff0000, v54
	v_lshlrev_b32_e32 v54, 16, v53
	v_and_b32_e32 v55, 0xffff0000, v53
	v_lshlrev_b32_e32 v102, 16, v52
	v_and_b32_e32 v103, 0xffff0000, v52
	v_exp_f32_e32 v39, v39
	v_exp_f32_e32 v136, v104
	v_exp_f32_e32 v137, v105
	v_exp_f32_e32 v138, v106
	v_exp_f32_e32 v139, v107
	v_exp_f32_e32 v140, v108
	s_waitcnt vmcnt(7)
	v_lshlrev_b32_e32 v52, 16, v59
	v_and_b32_e32 v53, 0xffff0000, v59
	v_lshlrev_b32_e32 v104, 16, v58
	v_and_b32_e32 v105, 0xffff0000, v58
	v_lshlrev_b32_e32 v58, 16, v57
	v_and_b32_e32 v59, 0xffff0000, v57
	v_lshlrev_b32_e32 v106, 16, v56
	v_and_b32_e32 v107, 0xffff0000, v56
	v_exp_f32_e32 v141, v109
	v_exp_f32_e32 v142, v110
	s_waitcnt vmcnt(6)
	v_lshlrev_b32_e32 v56, 16, v63
	v_and_b32_e32 v57, 0xffff0000, v63
	v_lshlrev_b32_e32 v108, 16, v62
	v_and_b32_e32 v109, 0xffff0000, v62
	v_lshlrev_b32_e32 v62, 16, v61
	v_and_b32_e32 v63, 0xffff0000, v61
	v_lshlrev_b32_e32 v110, 16, v60
	v_and_b32_e32 v111, 0xffff0000, v60
	s_waitcnt vmcnt(5)
	v_lshlrev_b32_e32 v60, 16, v67
	v_and_b32_e32 v61, 0xffff0000, v67
	v_lshlrev_b32_e32 v112, 16, v66
	v_and_b32_e32 v113, 0xffff0000, v66
	v_lshlrev_b32_e32 v66, 16, v65
	v_and_b32_e32 v67, 0xffff0000, v65
	v_lshlrev_b32_e32 v114, 16, v64
	v_and_b32_e32 v115, 0xffff0000, v64
	v_mul_f32_e32 v122, 0xbfb8aa3b, v108
	v_mul_f32_e32 v123, 0xbfb8aa3b, v109
	v_mul_f32_e32 v124, 0xbfb8aa3b, v62
	v_mul_f32_e32 v125, 0xbfb8aa3b, v63
	v_mul_f32_e32 v126, 0xbfb8aa3b, v110
	v_mul_f32_e32 v127, 0xbfb8aa3b, v111
	s_waitcnt vmcnt(4)
	v_lshlrev_b32_e32 v64, 16, v71
	v_and_b32_e32 v65, 0xffff0000, v71
	v_lshlrev_b32_e32 v116, 16, v70
	v_and_b32_e32 v117, 0xffff0000, v70
	v_lshlrev_b32_e32 v70, 16, v69
	v_and_b32_e32 v71, 0xffff0000, v69
	v_lshlrev_b32_e32 v118, 16, v68
	v_and_b32_e32 v119, 0xffff0000, v68
	v_mul_f32_e32 v128, 0xbfb8aa3b, v60
	v_mul_f32_e32 v129, 0xbfb8aa3b, v61
	v_mul_f32_e32 v130, 0xbfb8aa3b, v112
	v_mul_f32_e32 v131, 0xbfb8aa3b, v113
	v_mul_f32_e32 v132, 0xbfb8aa3b, v66
	v_mul_f32_e32 v133, 0xbfb8aa3b, v67
	v_mul_f32_e32 v134, 0xbfb8aa3b, v114
	v_mul_f32_e32 v135, 0xbfb8aa3b, v115
	s_waitcnt vmcnt(2)
	v_lshlrev_b32_e32 v68, 16, v79
	v_and_b32_e32 v69, 0xffff0000, v79
	v_lshlrev_b32_e32 v120, 16, v78
	v_and_b32_e32 v121, 0xffff0000, v78
	v_exp_f32_e32 v153, v122
	v_exp_f32_e32 v154, v123
	v_lshlrev_b32_e32 v78, 16, v77
	v_and_b32_e32 v79, 0xffff0000, v77
	v_exp_f32_e32 v155, v124
	v_exp_f32_e32 v156, v125
	v_lshlrev_b32_e32 v122, 16, v76
	v_and_b32_e32 v123, 0xffff0000, v76
	v_exp_f32_e32 v157, v126
	v_exp_f32_e32 v159, v127
	v_lshlrev_b32_e32 v76, 16, v75
	v_and_b32_e32 v77, 0xffff0000, v75
	v_lshlrev_b32_e32 v124, 16, v74
	v_and_b32_e32 v125, 0xffff0000, v74
	v_lshlrev_b32_e32 v74, 16, v73
	v_and_b32_e32 v75, 0xffff0000, v73
	v_lshlrev_b32_e32 v126, 16, v72
	v_and_b32_e32 v127, 0xffff0000, v72
	v_exp_f32_e32 v160, v128
	v_exp_f32_e32 v161, v129
	v_exp_f32_e32 v162, v130
	v_exp_f32_e32 v163, v131
	v_exp_f32_e32 v164, v132
	v_exp_f32_e32 v165, v133
	v_exp_f32_e32 v166, v134
	v_exp_f32_e32 v167, v135
	s_waitcnt vmcnt(0)
	v_lshlrev_b32_e32 v72, 16, v87
	v_and_b32_e32 v73, 0xffff0000, v87
	v_lshlrev_b32_e32 v128, 16, v86
	v_and_b32_e32 v129, 0xffff0000, v86
	v_lshlrev_b32_e32 v86, 16, v85
	v_and_b32_e32 v87, 0xffff0000, v85
	v_lshlrev_b32_e32 v130, 16, v84
	v_and_b32_e32 v131, 0xffff0000, v84
	v_lshlrev_b32_e32 v84, 16, v83
	v_and_b32_e32 v85, 0xffff0000, v83
	v_lshlrev_b32_e32 v132, 16, v82
	v_and_b32_e32 v133, 0xffff0000, v82
	v_lshlrev_b32_e32 v82, 16, v81
	v_and_b32_e32 v83, 0xffff0000, v81
	v_lshlrev_b32_e32 v134, 16, v80
	v_and_b32_e32 v135, 0xffff0000, v80
	v_pk_add_f32 v[54:55], v[74:75], v[54:55]
	v_pk_add_f32 v[74:75], v[126:127], v[102:103]
	v_add_f32_e32 v39, 1.0, v39
	v_pk_add_f32 v[50:51], v[86:87], v[50:51]
	v_add_f32_e32 v126, 1.0, v137
	v_add_f32_e32 v127, 1.0, v138
	v_pk_add_f32 v[86:87], v[130:131], v[98:99]
	v_add_f32_e32 v130, 1.0, v139
	v_add_f32_e32 v131, 1.0, v140
	v_pk_add_f32 v[52:53], v[84:85], v[52:53]
	v_pk_add_f32 v[84:85], v[132:133], v[104:105]
	v_pk_add_f32 v[58:59], v[82:83], v[58:59]
	v_pk_add_f32 v[82:83], v[134:135], v[106:107]
	v_pk_mul_f32 v[104:105], v[74:75], v[74:75]
	v_pk_add_f32 v[42:43], v[78:79], v[42:43]
	v_pk_add_f32 v[78:79], v[122:123], v[92:93]
	v_pk_mul_f32 v[102:103], v[54:55], v[54:55]
	v_rcp_f32_e32 v122, v39
	v_rcp_f32_e32 v126, v126
	v_rcp_f32_e32 v127, v127
	v_rcp_f32_e32 v130, v130
	v_rcp_f32_e32 v131, v131
	v_pk_mul_f32 v[138:139], v[82:83], v[82:83]
	v_add_f32_e32 v39, v104, v105
	v_pk_add_f32 v[48:49], v[76:77], v[48:49]
	v_pk_add_f32 v[76:77], v[124:125], v[100:101]
	v_add_f32_e32 v123, 1.0, v136
	v_pk_mul_f32 v[136:137], v[58:59], v[58:59]
	v_add_f32_e32 v104, v138, v139
	v_add_f32_e32 v39, v102, v39
	v_pk_mul_f32 v[100:101], v[76:77], v[76:77]
	v_add_f32_e32 v105, 1.0, v153
	v_add_f32_e32 v138, 1.0, v154
	v_add_f32_e32 v136, v136, v104
	v_add_f32_e32 v39, v103, v39
	v_pk_mul_f32 v[134:135], v[84:85], v[84:85]
	v_rcp_f32_e32 v104, v105
	v_rcp_f32_e32 v105, v138
	v_add_f32_e32 v136, v137, v136
	v_add_f32_e32 v39, v100, v39
	v_pk_mul_f32 v[98:99], v[48:49], v[48:49]
	v_pk_mul_f32 v[96:97], v[126:127], v[96:97]
	v_pk_mul_f32 v[126:127], v[130:131], v[44:45]
	v_add_f32_e32 v44, v134, v136
	v_add_f32_e32 v39, v101, v39
	v_pk_mul_f32 v[132:133], v[52:53], v[52:53]
	v_add_f32_e32 v44, v135, v44
	v_add_f32_e32 v39, v98, v39
	v_pk_add_f32 v[40:41], v[72:73], v[40:41]
	v_pk_add_f32 v[72:73], v[128:129], v[94:95]
	v_pk_mul_f32 v[94:95], v[78:79], v[78:79]
	v_add_f32_e32 v130, v132, v44
	v_add_f32_e32 v39, v99, v39
	v_pk_mul_f32 v[128:129], v[86:87], v[86:87]
	v_pk_mul_f32 v[44:45], v[104:105], v[108:109]
	v_add_f32_e32 v108, v133, v130
	v_add_f32_e32 v39, v94, v39
	v_pk_mul_f32 v[92:93], v[42:43], v[42:43]
	v_add_f32_e32 v94, v128, v108
	v_add_f32_e32 v39, v95, v39
	v_pk_add_f32 v[80:81], v[120:121], v[90:91]
	v_pk_mul_f32 v[124:125], v[50:51], v[50:51]
	v_add_f32_e32 v94, v129, v94
	v_add_f32_e32 v39, v92, v39
	v_pk_mul_f32 v[90:91], v[80:81], v[80:81]
	v_add_f32_e32 v92, v124, v94
	v_add_f32_e32 v39, v93, v39
	v_pk_add_f32 v[68:69], v[68:69], v[88:89]
	v_pk_mul_f32 v[120:121], v[72:73], v[72:73]
	v_add_f32_e32 v92, v125, v92
	v_add_f32_e32 v39, v90, v39
	v_pk_mul_f32 v[88:89], v[68:69], v[68:69]
	v_add_f32_e32 v90, v120, v92
	v_add_f32_e32 v39, v91, v39
	v_pk_mul_f32 v[106:107], v[40:41], v[40:41]
	v_add_f32_e32 v90, v121, v90
	v_add_f32_e32 v39, v88, v39
	v_add_f32_e32 v88, v106, v90
	v_add_f32_e32 v39, v89, v39
	v_add_f32_e32 v88, v107, v88
	ds_bpermute_b32 v89, v34, v39
	ds_bpermute_b32 v90, v34, v88
	v_mul_f32_e32 v143, 0xbfb8aa3b, v56
	v_mul_f32_e32 v144, 0xbfb8aa3b, v57
	v_mul_f32_e32 v145, 0xbfb8aa3b, v64
	s_waitcnt lgkmcnt(1)
	v_add_f32_e32 v39, v39, v89
	s_waitcnt lgkmcnt(0)
	v_add_f32_e32 v88, v88, v90
	ds_bpermute_b32 v89, v35, v39
	ds_bpermute_b32 v90, v35, v88
	v_mul_f32_e32 v146, 0xbfb8aa3b, v65
	v_mul_f32_e32 v147, 0xbfb8aa3b, v116
	v_mul_f32_e32 v148, 0xbfb8aa3b, v117
	s_waitcnt lgkmcnt(1)
	v_add_f32_e32 v39, v39, v89
	s_waitcnt lgkmcnt(0)
	v_add_f32_e32 v88, v88, v90
	ds_bpermute_b32 v89, v36, v39
	ds_bpermute_b32 v90, v36, v88
	v_mul_f32_e32 v149, 0xbfb8aa3b, v70
	v_mul_f32_e32 v150, 0xbfb8aa3b, v71
	v_mul_f32_e32 v151, 0xbfb8aa3b, v118
	s_waitcnt lgkmcnt(1)
	v_add_f32_e32 v39, v39, v89
	s_waitcnt lgkmcnt(0)
	v_add_f32_e32 v88, v88, v90
	ds_bpermute_b32 v89, v37, v39
	ds_bpermute_b32 v90, v37, v88
	v_mul_f32_e32 v152, 0xbfb8aa3b, v119
	v_exp_f32_e32 v143, v143
	v_exp_f32_e32 v144, v144
	s_waitcnt lgkmcnt(1)
	v_add_f32_e32 v39, v39, v89
	s_waitcnt lgkmcnt(0)
	v_add_f32_e32 v88, v88, v90
	v_fmamk_f32 v39, v39, 0x3b800000, v17
	v_fmamk_f32 v88, v88, 0x3b800000, v17
	v_mul_f32_e32 v89, 0x4f800000, v39
	v_cmp_gt_f32_e64 s[6:7], s37, v39
	v_mul_f32_e32 v90, 0x4f800000, v88
	v_cmp_gt_f32_e32 vcc, s37, v88
	v_cndmask_b32_e64 v39, v39, v89, s[6:7]
	v_sqrt_f32_e32 v89, v39
	v_cndmask_b32_e32 v88, v88, v90, vcc
	v_sqrt_f32_e32 v90, v88
	v_exp_f32_e32 v145, v145
	v_add_u32_e32 v91, -1, v89
	v_add_u32_e32 v92, 1, v89
	v_add_u32_e32 v93, -1, v90
	v_fma_f32 v95, -v91, v89, v39
	v_add_u32_e32 v94, 1, v90
	v_fma_f32 v106, -v92, v89, v39
	v_fma_f32 v107, -v93, v90, v88
	v_cmp_ge_f32_e64 s[8:9], 0, v95
	v_fma_f32 v108, -v94, v90, v88
	v_cmp_lt_f32_e64 s[10:11], 0, v106
	v_cndmask_b32_e64 v89, v89, v91, s[8:9]
	v_cmp_ge_f32_e64 s[8:9], 0, v107
	v_cndmask_b32_e64 v89, v89, v92, s[10:11]
	v_mul_f32_e32 v91, 0x37800000, v89
	v_cndmask_b32_e64 v90, v90, v93, s[8:9]
	v_cmp_lt_f32_e64 s[8:9], 0, v108
	v_cndmask_b32_e64 v89, v89, v91, s[6:7]
	v_cmp_class_f32_e64 s[6:7], v39, v38
	v_cndmask_b32_e64 v90, v90, v94, s[8:9]
	v_mul_f32_e32 v92, 0x37800000, v90
	v_cndmask_b32_e32 v90, v90, v92, vcc
	v_cmp_class_f32_e32 vcc, v88, v38
	v_cndmask_b32_e64 v39, v89, v39, s[6:7]
	v_exp_f32_e32 v146, v146
	v_cndmask_b32_e32 v89, v90, v88, vcc
	v_div_scale_f32 v88, s[6:7], v39, v39, 1.0
	v_div_scale_f32 v91, s[6:7], v89, v89, 1.0
	v_rcp_f32_e32 v93, v88
	v_rcp_f32_e32 v94, v91
	v_exp_f32_e32 v147, v147
	v_exp_f32_e32 v148, v148
	v_fma_f32 v95, -v88, v93, 1.0
	v_exp_f32_e32 v149, v149
	v_exp_f32_e32 v150, v150
	v_exp_f32_e32 v151, v151
	v_exp_f32_e32 v152, v152
	v_div_scale_f32 v90, vcc, 1.0, v39, 1.0
	v_fma_f32 v106, -v91, v94, 1.0
	v_fmac_f32_e32 v93, v95, v93
	v_div_scale_f32 v92, s[6:7], 1.0, v89, 1.0
	v_fmac_f32_e32 v94, v106, v94
	v_mul_f32_e32 v95, v90, v93
	v_mul_f32_e32 v106, v92, v94
	v_fma_f32 v107, -v88, v95, v90
	v_add_f32_e32 v140, 1.0, v141
	v_add_f32_e32 v141, 1.0, v142
	v_add_f32_e32 v139, 1.0, v155
	v_add_f32_e32 v142, 1.0, v156
	v_add_f32_e32 v153, 1.0, v157
	v_add_f32_e32 v154, 1.0, v159
	v_add_f32_e32 v155, 1.0, v160
	v_add_f32_e32 v156, 1.0, v161
	v_add_f32_e32 v157, 1.0, v162
	v_add_f32_e32 v159, 1.0, v163
	v_add_f32_e32 v160, 1.0, v164
	v_add_f32_e32 v161, 1.0, v165
	v_add_f32_e32 v162, 1.0, v166
	v_add_f32_e32 v163, 1.0, v167
	v_add_f32_e32 v102, 1.0, v143
	v_add_f32_e32 v164, 1.0, v144
	v_fma_f32 v108, -v91, v106, v92
	v_fmac_f32_e32 v95, v107, v93
	v_rcp_f32_e32 v123, v123
	v_add_f32_e32 v165, 1.0, v145
	v_add_f32_e32 v166, 1.0, v146
	v_add_f32_e32 v167, 1.0, v147
	v_add_f32_e32 v168, 1.0, v148
	v_add_f32_e32 v169, 1.0, v149
	v_add_f32_e32 v170, 1.0, v150
	v_add_f32_e32 v171, 1.0, v151
	v_add_f32_e32 v172, 1.0, v152
	v_rcp_f32_e32 v138, v139
	v_rcp_f32_e32 v139, v142
	v_rcp_f32_e32 v144, v155
	v_rcp_f32_e32 v145, v156
	v_rcp_f32_e32 v146, v157
	v_rcp_f32_e32 v147, v159
	v_rcp_f32_e32 v148, v160
	v_rcp_f32_e32 v149, v161
	v_rcp_f32_e32 v150, v162
	v_rcp_f32_e32 v151, v163
	v_rcp_f32_e32 v102, v102
	v_rcp_f32_e32 v103, v164
	v_fmac_f32_e32 v106, v108, v94
	v_fma_f32 v88, -v88, v95, v90
	v_rcp_f32_e32 v142, v153
	v_rcp_f32_e32 v143, v154
	v_rcp_f32_e32 v152, v165
	v_rcp_f32_e32 v153, v166
	v_rcp_f32_e32 v154, v167
	v_rcp_f32_e32 v155, v168
	v_rcp_f32_e32 v156, v169
	v_rcp_f32_e32 v157, v170
	v_rcp_f32_e32 v160, v171
	v_rcp_f32_e32 v161, v172
	v_fma_f32 v90, -v91, v106, v92
	v_div_fmas_f32 v88, v88, v93, v95
	s_mov_b64 vcc, s[6:7]
	v_rcp_f32_e32 v140, v140
	v_rcp_f32_e32 v141, v141
	v_div_fixup_f32 v88, v88, v39, 1.0
	v_div_fmas_f32 v39, v90, v94, v106
	v_pk_mul_f32 v[74:75], v[74:75], v[88:89] op_sel_hi:[1,0]
	v_pk_mul_f32 v[54:55], v[54:55], v[88:89] op_sel_hi:[1,0]
	v_pk_mul_f32 v[76:77], v[76:77], v[88:89] op_sel_hi:[1,0]
	v_pk_mul_f32 v[48:49], v[48:49], v[88:89] op_sel_hi:[1,0]
	v_pk_mul_f32 v[78:79], v[78:79], v[88:89] op_sel_hi:[1,0]
	v_pk_mul_f32 v[42:43], v[42:43], v[88:89] op_sel_hi:[1,0]
	v_pk_mul_f32 v[80:81], v[80:81], v[88:89] op_sel_hi:[1,0]
	v_pk_mul_f32 v[68:69], v[68:69], v[88:89] op_sel_hi:[1,0]
	v_div_fixup_f32 v88, v39, v89, 1.0
	v_pk_mul_f32 v[122:123], v[122:123], v[46:47]
	v_pk_mul_f32 v[46:47], v[138:139], v[62:63]
	v_pk_mul_f32 v[60:61], v[144:145], v[60:61]
	v_pk_mul_f32 v[100:101], v[146:147], v[112:113]
	v_pk_mul_f32 v[66:67], v[148:149], v[66:67]
	v_pk_mul_f32 v[104:105], v[150:151], v[114:115]
	v_pk_mul_f32 v[56:57], v[102:103], v[56:57]
	v_pk_mul_f32 v[74:75], v[12:13], v[74:75]
	v_pk_mul_f32 v[54:55], v[14:15], v[54:55]
	v_pk_mul_f32 v[76:77], v[8:9], v[76:77]
	v_pk_mul_f32 v[48:49], v[10:11], v[48:49]
	v_pk_mul_f32 v[42:43], v[6:7], v[42:43]
	v_pk_mul_f32 v[68:69], v[2:3], v[68:69]
	v_pk_mul_f32 v[82:83], v[82:83], v[88:89] op_sel_hi:[1,0]
	v_pk_mul_f32 v[58:59], v[58:59], v[88:89] op_sel_hi:[1,0]
	v_pk_mul_f32 v[84:85], v[84:85], v[88:89] op_sel_hi:[1,0]
	v_pk_mul_f32 v[52:53], v[52:53], v[88:89] op_sel_hi:[1,0]
	v_pk_mul_f32 v[62:63], v[142:143], v[110:111]
	v_pk_mul_f32 v[64:65], v[152:153], v[64:65]
	v_pk_mul_f32 v[98:99], v[154:155], v[116:117]
	v_pk_mul_f32 v[70:71], v[156:157], v[70:71]
	v_pk_mul_f32 v[102:103], v[160:161], v[118:119]
	v_pk_mul_f32 v[78:79], v[4:5], v[78:79]
	v_pk_mul_f32 v[80:81], v[0:1], v[80:81]
	v_pk_mul_f32 v[86:87], v[86:87], v[88:89] op_sel_hi:[1,0]
	v_pk_mul_f32 v[50:51], v[50:51], v[88:89] op_sel_hi:[1,0]
	v_pk_mul_f32 v[72:73], v[72:73], v[88:89] op_sel_hi:[1,0]
	v_pk_mul_f32 v[40:41], v[40:41], v[88:89] op_sel_hi:[1,0]
	v_pk_mul_f32 v[74:75], v[104:105], v[74:75]
	v_pk_mul_f32 v[54:55], v[66:67], v[54:55]
	v_pk_mul_f32 v[66:67], v[100:101], v[76:77]
	v_pk_mul_f32 v[48:49], v[60:61], v[48:49]
	v_pk_mul_f32 v[46:47], v[46:47], v[42:43]
	v_pk_mul_f32 v[56:57], v[56:57], v[68:69]
	v_pk_mul_f32 v[68:69], v[12:13], v[82:83]
	v_pk_mul_f32 v[58:59], v[14:15], v[58:59]
	v_pk_mul_f32 v[76:77], v[8:9], v[84:85]
	v_pk_mul_f32 v[52:53], v[10:11], v[52:53]
	v_pk_mul_f32 v[28:29], v[140:141], v[28:29]
	v_pk_mul_f32 v[60:61], v[62:63], v[78:79]
	v_pk_mul_f32 v[62:63], v[44:45], v[80:81]
	v_pk_mul_f32 v[78:79], v[4:5], v[86:87]
	v_pk_mul_f32 v[50:51], v[6:7], v[50:51]
	v_pk_mul_f32 v[72:73], v[0:1], v[72:73]
	v_pk_mul_f32 v[80:81], v[2:3], v[40:41]
	v_cvt_pk_bf16_f32 v40, v74, v75
	v_cvt_pk_bf16_f32 v41, v54, v55
	v_cvt_pk_bf16_f32 v42, v66, v67
	v_cvt_pk_bf16_f32 v43, v48, v49
	v_cvt_pk_bf16_f32 v45, v46, v47
	v_cvt_pk_bf16_f32 v47, v56, v57
	v_pk_mul_f32 v[48:49], v[102:103], v[68:69]
	v_pk_mul_f32 v[54:55], v[70:71], v[58:59]
	v_pk_mul_f32 v[56:57], v[98:99], v[76:77]
	v_pk_mul_f32 v[52:53], v[64:65], v[52:53]
	v_cvt_pk_bf16_f32 v44, v60, v61
	v_cvt_pk_bf16_f32 v46, v62, v63
	v_pk_mul_f32 v[58:59], v[126:127], v[78:79]
	v_pk_mul_f32 v[50:51], v[96:97], v[50:51]
	v_pk_mul_f32 v[60:61], v[122:123], v[72:73]
	v_pk_mul_f32 v[62:63], v[28:29], v[80:81]
	global_store_dwordx4 v[26:27], v[40:43], off offset:-4096
	global_store_dwordx4 v[30:31], v[44:47], off offset:16
	v_cvt_pk_bf16_f32 v28, v48, v49
	v_cvt_pk_bf16_f32 v29, v54, v55
	v_cvt_pk_bf16_f32 v30, v56, v57
	v_cvt_pk_bf16_f32 v31, v52, v53
	v_cvt_pk_bf16_f32 v40, v58, v59
	v_cvt_pk_bf16_f32 v41, v50, v51
	v_cvt_pk_bf16_f32 v42, v60, v61
	v_cvt_pk_bf16_f32 v43, v62, v63
	global_store_dwordx4 v[26:27], v[28:31], off
	global_store_dwordx4 v[26:27], v[40:43], off offset:16
	s_andn2_b64 exec, exec, s[22:23]
	s_cbranch_execnz .LBB0_409
